# split barriers: the XCD leader issues the L2 write-back without waiting and bumps the completion word one tile / one chunk later
# baseline (speedup 1.0000x reference)
.LBB0_241:
	s_cmp_eq_u32 s8, 2
	s_cbranch_scc0 .Lsb_a2_n3
	s_and_saveexec_b64 s[100:101], s[56:57]
	s_cbranch_execz .Lsb_a2_x
	v_mov_b32_e32 v246, 0x20ff0
	ds_read_b32 v246, v246
	s_waitcnt vmcnt(16) lgkmcnt(0)
	v_add_u32_e32 v247, 1, v247
	v_cmp_eq_u32_e32 vcc, v247, v246
	s_cbranch_vccz .Lsb_a2_x
	buffer_wbl2 sc1
	s_or_b64 exec, exec, s[100:101]
	s_mov_b32 s99, 4
	s_branch .Lsb_a2_skip
.Lsb_a2_x:
	s_or_b64 exec, exec, s[100:101]
	s_mov_b32 s99, 0
	s_branch .Lsb_a2_skip
.Lsb_a2_n3:
	s_cmp_eq_u32 s8, 3
	s_cbranch_scc0 .Lsb_a2_skip
	s_cmp_eq_u32 s99, 4
	s_cbranch_scc0 .Lsb_a2_skip
	s_and_saveexec_b64 s[100:101], s[56:57]
	s_cbranch_execz .Lsb_a3_x
	s_waitcnt vmcnt(16)
	v_readlane_b32 s98, v242, 47
	s_nop 3
	s_cmp_eq_u32 s98, 0
	s_cselect_b32 s98, 0, 8
	s_add_u32 s98, s98, 0x16370d00
	s_add_u32 s98, s68, s98
	s_addc_u32 s99, s69, 0
	v_mov_b32_e32 v246, 0
	v_mov_b32_e32 v247, 1
	global_atomic_add v246, v247, s[98:99]
.Lsb_a3_x:
	s_or_b64 exec, exec, s[100:101]
	s_mov_b32 s99, 0
.Lsb_a2_skip:
	s_andn2_b64 vcc, exec, s[42:43]
	s_mov_b32 s10, s50
	s_mov_b32 s9, s52
	s_mov_b64 s[72:73], s[58:59]
	s_mov_b64 s[42:43], s[54:55]
	s_cbranch_vccz .LBB0_251

.LBB0_355:
	s_or_b64 exec, exec, s[46:47]
	s_andn2_b64 vcc, exec, s[48:49]
	s_cbranch_vccnz .LBB0_359
	s_xor_b32 s7, s4, 1
	s_mulk_i32 s7, 0x4a40
	s_add_i32 s7, s7, 0
	s_waitcnt lgkmcnt(3)
	v_add3_u32 v0, s7, v89, v90
	s_waitcnt vmcnt(0)
	s_cmp_eq_u32 s99, 0
	s_cbranch_scc1 .Lnb_skip
	s_cmp_eq_u32 s99, 4
	s_cbranch_scc1 .Lnb_bump
	s_and_saveexec_b64 s[100:101], s[56:57]
	s_cbranch_execz .Lnb_x1
	v_mov_b32_e32 v246, 0x20ff0
	ds_read_b32 v246, v246
	s_waitcnt vmcnt(0) lgkmcnt(0)
	v_add_u32_e32 v247, 1, v247
	v_cmp_eq_u32_e32 vcc, v247, v246
	s_cbranch_vccz .Lnb_x1
	buffer_wbl2 sc1
	s_or_b64 exec, exec, s[100:101]
	s_mov_b32 s99, 4
	s_branch .Lnb_skip

.Lnb_bump:
	s_and_saveexec_b64 s[100:101], s[56:57]
	s_cbranch_execz .Lnb_xb
	v_readlane_b32 s98, v242, 47
	s_nop 3
	s_cmp_eq_u32 s98, 0
	s_cselect_b32 s98, 0, 8
	s_add_u32 s98, s98, 0x16370d04
	s_add_u32 s98, s68, s98
	s_addc_u32 s99, s69, 0
	v_mov_b32_e32 v246, 0
	v_mov_b32_e32 v247, 1
	global_atomic_add v246, v247, s[98:99]

.LBB0_361:
	s_waitcnt vmcnt(0)
	s_cmp_eq_u32 s99, 4
	s_cbranch_scc0 .Lnb2_n
	s_and_saveexec_b64 s[100:101], s[56:57]
	s_cbranch_execz .Lnb2_xb
	v_readlane_b32 s98, v242, 47
	s_nop 3
	s_cmp_eq_u32 s98, 0
	s_cselect_b32 s98, 0, 8
	s_add_u32 s98, s98, 0x16370d04
	s_add_u32 s98, s68, s98
	s_addc_u32 s99, s69, 0
	v_mov_b32_e32 v246, 0
	v_mov_b32_e32 v247, 1
	global_atomic_add v246, v247, s[98:99]
	s_waitcnt vmcnt(0)

.Lnb2_n:
	s_cmp_eq_u32 s99, 0
	s_cbranch_scc1 .Lsb_c2_skip
	s_mov_b32 s99, 0
	s_and_saveexec_b64 s[100:101], s[56:57]
	s_cbranch_execz .Lsb_c2_x
	v_mov_b32_e32 v246, 0x20ff0
	ds_read_b32 v246, v246
	s_waitcnt vmcnt(0) lgkmcnt(0)
	v_add_u32_e32 v247, 1, v247
	v_cmp_eq_u32_e32 vcc, v247, v246
	s_cbranch_vccz .Lsb_c2_x
	buffer_wbl2 sc1
	s_waitcnt vmcnt(0)
	v_readlane_b32 s98, v242, 47
	s_nop 3
	s_cmp_eq_u32 s98, 0
	s_cselect_b32 s98, 0, 8
	s_add_u32 s98, s98, 0x16370d04
	s_add_u32 s98, s68, s98
	s_addc_u32 s99, s69, 0
	v_mov_b32_e32 v246, 0
	v_mov_b32_e32 v247, 1
	global_atomic_add v246, v247, s[98:99]
	s_waitcnt vmcnt(0)
